# kmax pass moved out of the 16 fox_cumsum units into 64 separate P2 queue units (4 partial maxima per head, fox units max them)
# speedup vs baseline: 1.0600x; 1.0079x over previous
; #define otid() otid_(wbase)
; __global__ void __launch_bounds__(NTHR) mega(Params p) {
;     ...
;         int* my = ctr + 8 + phase_id;
;         for (;;) {
;           __syncthreads();
;           if (otid() == 0) s_unit = atomicAdd(my, 1);
;           __syncthreads();
;           const int u0 = s_unit;
;           const int n_fill = (hf == 0 && layer > 0) ? 256 : 0;
;           int u = u0;
;           if (u >= 784 + n_fill) break;
.LBB0_233:
	s_or_b64 exec, exec, s[0:1]
	s_xor_b64 s[0:1], s[8:9], -1
	v_writelane_b32 v254, s0, 43
	s_waitcnt lgkmcnt(0)
	s_barrier
	v_writelane_b32 v254, s1, 44
	s_nop 0
	v_readlane_b32 s0, v254, 9
	v_readlane_b32 s1, v254, 10
	s_mov_b32 s4, s0
	s_ashr_i32 s5, s0, 31
	v_writelane_b32 v254, s0, 9
	s_lshl_b64 s[14:15], s[4:5], 2
	s_nop 0
	v_writelane_b32 v254, s1, 10
	v_readlane_b32 s0, v253, 26
	s_add_u32 s16, s0, s14
	v_readlane_b32 s0, v253, 27
	s_addc_u32 s17, s0, s15
	v_readlane_b32 s0, v254, 26
	v_readlane_b32 s1, v254, 27
	s_and_b64 s[0:1], s[0:1], s[8:9]
	s_and_b64 s[0:1], s[0:1], exec
	s_cselect_b32 s13, 0x100, 0
	s_add_i32 s56, s13, 0x350
	s_or_b32 s57, s13, 16
	s_lshl_b32 s68, s12, 14
	s_branch .LBB0_237

; DI void unpack8(uint4 v, float* f) { f[0] = bflo(v.x); f[1] = bfhi(v.x); f[2] = bflo(v.y); f[3] = bfhi(v.y); f[4] = bflo(v.z); f[5] = bfhi(v.z); f[6] = bflo(v.w); f[7] = bfhi(v.w); }
; DI float ex2(float x) { return __builtin_amdgcn_exp2f(x); }
; DI void norm_unit(const Params& p, int layer, int half, int nu, int tid) { norm_rows(p, layer, half * HROWS + nu * 64, 64, 0, 8, tid); }
; #define otid() otid_(wbase)
; DI void ret_local_unit(const Params& p, int hf, int bl, int c, int hd, unsigned char* shm, int tid) {
;     ...
;   const float lg = logf(1.0f - ex2(-5.0f - (float)hd));
; #pragma unroll
;   for (int it = 0; it < 2; ++it) {
;     const int idx = tid + it * NTHR, j = idx >> 3, dg = idx & 7;
;     const bf16_t* base = projb + (size_t)(c * 128 + j) * NP;
;     float k1[8], k2[8]; unpack8(*(const uint4*)(base + C_RK + hd * 128 + dg * 8), k1); unpack8(*(const uint4*)(base + C_RK + hd * 128 + 64 + dg * 8), k2);
;     const float w = __expf(lg * (float)(127 - j)) * 0.08838834764831845f;
; __global__ void __launch_bounds__(NTHR) mega(Params p) {
;     ...
;           if (u >= 784 + n_fill) break;
;           if (u >= 16 && u < 16 + n_fill) { norm_unit(p, layer, 1, u - 16, otid()); continue; }
;           if (u >= 16) u -= n_fill;
;           if (u < 16) fox_cumsum_unit(p, hf, u >> 3, u & 7, shm, otid());
;           else if (u < 272) { const int k = u - 16; ssd_local_unit(p, layer, hf, k >> 7, (k >> 1) & 63, k & 1, shm, otid()); }
;           else { const int k = u - 272; ret_local_unit(p, hf, k >> 8, (k >> 2) & 63, k & 3, shm, otid()); }
.LBB0_241:
	s_or_b64 exec, exec, s[0:1]
	s_waitcnt lgkmcnt(0)
	s_barrier
	ds_read_b32 v0, v161 offset:16
	s_mov_b64 s[0:1], -1
	s_waitcnt lgkmcnt(0)
	v_cmp_le_i32_e32 vcc, s56, v0
	v_readfirstlane_b32 s58, v0
	s_cbranch_vccnz .LBB0_236
	s_cmp_gt_i32 s58, 15
	s_cselect_b64 s[0:1], -1, 0
	s_cmp_lt_i32 s58, s57
	s_cselect_b64 s[4:5], -1, 0
	s_and_b64 s[4:5], s[0:1], s[4:5]
	s_andn2_b64 vcc, exec, s[4:5]
	s_mov_b64 s[4:5], -1
	s_cbranch_vccz .LBB0_353
	s_and_b64 s[0:1], s[0:1], exec
	s_cselect_b32 s0, s13, 0
	s_sub_i32 s24, s58, s0
	s_cmp_gt_i32 s24, 15
	s_mov_b64 s[0:1], -1
	s_cbranch_scc0 .LBB0_312
	s_cmpk_gt_u32 s24, 0x10f
	s_cbranch_scc0 .LBB0_246
	s_cmpk_gt_u32 s24, 0x30f
	s_cbranch_scc1 .Lkmx_unit
	s_add_i32 s8, s24, 0xfffffef0
	s_lshr_b32 s4, s8, 8
	s_mul_i32 s2, s4, 0x3400000
	s_bfe_u32 s10, s8, 0x60002
	s_and_b32 s9, s58, 3
	s_lshl_b64 s[0:1], s[2:3], 1
	s_add_u32 s6, s38, s0
	s_addc_u32 s7, s39, s1
	s_lshl_b32 s0, s4, 13
	v_cvt_f32_ubyte0_e32 v0, s9
	s_add_i32 s0, s0, s68
	s_lshl_b32 s11, s10, 7
	v_sub_f32_e32 v0, 0xc0a00000, v0
	s_or_b32 s0, s0, s11
	v_exp_f32_e32 v0, v0
	s_lshl_b32 s2, s0, 6
	s_lshl_b64 s[0:1], s[2:3], 3
	v_readlane_b32 s2, v252, 45
	s_add_u32 s4, s2, s0
	v_readlane_b32 s0, v252, 46
	s_addc_u32 s5, s0, s1
	v_sub_f32_e32 v0, 1.0, v0
	s_mov_b32 s0, 0x800000
	v_cmp_gt_f32_e32 vcc, s0, v0
	s_and_b64 s[0:1], vcc, exec
	s_cselect_b32 s0, 32, 0
	v_ldexp_f32 v0, v0, s0
	v_log_f32_e32 v0, v0
	s_mov_b32 s0, 0x3f317217
	v_mov_b32_e32 v18, v163
	v_mul_f32_e32 v1, 0x3f317217, v0
	v_fma_f32 v1, v0, s0, -v1
	v_fmac_f32_e32 v1, 0x3377d1cf, v0
	s_mov_b32 s0, 0x7f800000
	v_fmac_f32_e32 v1, 0x3f317217, v0
	v_cmp_lt_f32_e64 s[0:1], |v0|, s0
	v_ashrrev_i32_e32 v13, 3, v18
	v_mov_b64_e32 v[14:15], s[6:7]
	v_cndmask_b32_e64 v0, v0, v1, s[0:1]
	v_cndmask_b32_e32 v1, 0, v201, vcc
	v_sub_f32_e32 v21, v0, v1
	v_and_b32_e32 v0, 7, v18
	v_lshlrev_b32_e32 v20, 3, v0
	v_lshlrev_b32_e32 v160, 4, v0
	v_lshlrev_b32_e32 v12, 5, v0
	v_add_u32_e32 v0, s11, v13
	v_mad_i64_i32 v[0:1], s[0:1], v0, s65, v[14:15]
	s_lshl_b32 s2, s9, 8
	v_lshl_add_u64 v[16:17], v[0:1], 0, s[2:3]
	v_lshl_add_u64 v[4:5], v[16:17], 0, v[160:161]
	v_lshl_add_u64 v[208:209], v[16:17], 0, v[160:161]
	global_load_dwordx4 v[100:103], v[208:209], off offset:1024
	global_load_dwordx4 v[104:107], v[208:209], off offset:1152
	v_lshl_or_b32 v210, v13, 6, v20
	v_mov_b32_e32 v211, v161
	v_lshl_add_u64 v[210:211], v[210:211], 3, s[4:5]
	global_load_dwordx4 v[108:111], v[210:211], off offset:48
	global_load_dwordx4 v[112:115], v[210:211], off offset:32
	global_load_dwordx4 v[116:119], v[210:211], off offset:16
	global_load_dwordx4 v[120:123], v[210:211], off
	v_mov_b32_e32 v212, v12
	v_mov_b32_e32 v213, v161
	v_lshl_add_u64 v[212:213], v[16:17], 0, v[212:213]
	global_load_dwordx4 v[124:127], v[212:213], off offset:2048
	global_load_dwordx4 v[128:131], v[212:213], off offset:2064
	v_add_u32_e32 v222, 64, v13
	v_add_u32_e32 v223, s11, v222
	v_mad_i64_i32 v[214:215], s[0:1], v223, s65, v[14:15]
	v_lshl_add_u64 v[214:215], v[214:215], 0, s[2:3]
	v_lshl_add_u64 v[216:217], v[214:215], 0, v[160:161]
	global_load_dwordx4 v[132:135], v[216:217], off offset:1024
	global_load_dwordx4 v[136:139], v[216:217], off offset:1152
	v_lshl_or_b32 v218, v222, 6, v20
	v_mov_b32_e32 v219, v161
	v_lshl_add_u64 v[218:219], v[218:219], 3, s[4:5]
	global_load_dwordx4 v[140:143], v[218:219], off offset:48
	global_load_dwordx4 v[144:147], v[218:219], off offset:32
	global_load_dwordx4 v[148:151], v[218:219], off offset:16
	global_load_dwordx4 v[152:155], v[218:219], off
	v_mov_b32_e32 v220, v12
	v_mov_b32_e32 v221, v161
	v_lshl_add_u64 v[220:221], v[214:215], 0, v[220:221]
	global_load_dwordx4 v[156:159], v[220:221], off offset:2048
	global_load_dwordx4 v[204:207], v[220:221], off offset:2064
	v_add_u32_e32 v19, 32, v12
	s_waitcnt vmcnt(15)
	v_mov_b32_e32 v0, v100
	v_mov_b32_e32 v1, v101
	v_mov_b32_e32 v2, v102
	v_mov_b32_e32 v3, v103
	v_lshlrev_b32_e32 v26, 16, v0
	v_and_b32_e32 v27, 0xffff0000, v0
	v_lshlrev_b32_e32 v28, 16, v1
	v_and_b32_e32 v29, 0xffff0000, v1
	v_lshlrev_b32_e32 v30, 16, v2
	v_and_b32_e32 v31, 0xffff0000, v2
	v_lshlrev_b32_e32 v32, 16, v3
	v_and_b32_e32 v33, 0xffff0000, v3
	s_waitcnt vmcnt(14)
	v_mov_b32_e32 v0, v104
	v_mov_b32_e32 v1, v105
	v_mov_b32_e32 v2, v106
	v_mov_b32_e32 v3, v107
	v_lshlrev_b32_e32 v34, 16, v0
	v_and_b32_e32 v35, 0xffff0000, v0
	v_sub_u32_e32 v0, 0x7f, v13
	v_cvt_f32_i32_e32 v0, v0
	v_lshlrev_b32_e32 v36, 16, v1
	v_and_b32_e32 v37, 0xffff0000, v1
	v_lshlrev_b32_e32 v38, 16, v2
	v_mul_f32_e32 v0, v21, v0
	v_mul_f32_e32 v0, 0x3fb8aa3b, v0
	v_exp_f32_e32 v0, v0
	v_and_b32_e32 v39, 0xffff0000, v2
	v_lshlrev_b32_e32 v40, 16, v3
	v_and_b32_e32 v41, 0xffff0000, v3
	v_mul_f32_e32 v42, 0x3db504f3, v0
	v_lshl_or_b32 v0, v13, 6, v20
	v_ashrrev_i32_e32 v1, 31, v0
	v_lshl_add_u64 v[22:23], v[0:1], 3, s[4:5]
	s_nop 0
	s_waitcnt vmcnt(10)
; DI void unpack8(uint4 v, float* f) { f[0] = bflo(v.x); f[1] = bfhi(v.x); f[2] = bflo(v.y); f[3] = bfhi(v.y); f[4] = bflo(v.z); f[5] = bfhi(v.z); f[6] = bflo(v.w); f[7] = bfhi(v.w); }
; DI uint4 pack8(const float* f) { uint4 r; r.x = pk2(f[0], f[1]); r.y = pk2(f[2], f[3]); r.z = pk2(f[4], f[5]); r.w = pk2(f[6], f[7]); return r; }
; DI void ret_local_unit(const Params& p, int hf, int bl, int c, int hd, unsigned char* shm, int tid) {
;     ...
; #pragma unroll
;   for (int it = 0; it < 2; ++it) {
;     const int idx = tid + it * NTHR, j = idx >> 3, dg = idx & 7;
;     const bf16_t* base = projb + (size_t)(c * 128 + j) * NP;
;     float k1[8], k2[8]; unpack8(*(const uint4*)(base + C_RK + hd * 128 + dg * 8), k1); unpack8(*(const uint4*)(base + C_RK + hd * 128 + 64 + dg * 8), k2);
;     const float w = __expf(lg * (float)(127 - j)) * 0.08838834764831845f;
;     float o1[8], o2[8];
; #pragma unroll
;     for (int e = 0; e < 8; ++e) {
;       const float2 t = cs[j * 64 + dg * 8 + e];
;       o1[e] = (k1[e] * t.x - k2[e] * t.y) * w; o2[e] = (k1[e] * t.y + k2[e] * t.x) * w;
;     }
;     *(uint4*)(sK + j * LD + dg * 8) = pack8(o1); *(uint4*)(sK + j * LD + 64 + dg * 8) = pack8(o2);
;     *(uint4*)(sV + j * LD + dg * 16) = *(const uint4*)(base + C_RV + hd * 128 + dg * 16);
;     *(uint4*)(sV + j * LD + dg * 16 + 8) = *(const uint4*)(base + C_RV + hd * 128 + dg * 16 + 8);
;   }
;   __syncthreads();
	v_mov_b32_e32 v0, v108
	v_mov_b32_e32 v1, v109
	v_mov_b32_e32 v2, v110
	v_mov_b32_e32 v3, v111
	v_mov_b32_e32 v4, v112
	v_mov_b32_e32 v5, v113
	v_mov_b32_e32 v6, v114
	v_mov_b32_e32 v7, v115
	v_mov_b32_e32 v8, v116
	v_mov_b32_e32 v9, v117
	v_mov_b32_e32 v10, v118
	v_mov_b32_e32 v11, v119
	v_mov_b32_e32 v22, v120
	v_mov_b32_e32 v23, v121
	v_mov_b32_e32 v24, v122
	v_mov_b32_e32 v25, v123
	v_mul_f32_e32 v43, v23, v34
	v_mul_f32_e32 v23, v23, v26
	v_fmac_f32_e32 v23, v22, v34
	v_fma_f32 v43, v22, v26, -v43
	v_mul_f32_e32 v22, v42, v23
	v_mul_f32_e32 v23, v25, v35
	v_mul_f32_e32 v25, v25, v27
	v_fmac_f32_e32 v25, v24, v35
	v_fma_f32 v23, v24, v27, -v23
	v_mul_f32_e32 v24, v42, v25
	v_mul_f32_e32 v25, v9, v36
	v_mul_f32_e32 v9, v9, v28
	v_fmac_f32_e32 v9, v8, v36
	v_fma_f32 v25, v8, v28, -v25
	v_mul_f32_e32 v8, v42, v9
	v_mul_f32_e32 v9, v11, v37
	v_mul_f32_e32 v11, v11, v29
	v_fmac_f32_e32 v11, v10, v37
	v_fma_f32 v9, v10, v29, -v9
	v_mul_f32_e32 v10, v42, v11
	v_mul_f32_e32 v11, v5, v38
	v_mul_f32_e32 v5, v5, v30
	v_fmac_f32_e32 v5, v4, v38
	v_fma_f32 v11, v4, v30, -v11
	v_mul_f32_e32 v4, v42, v5
	v_mul_f32_e32 v5, v7, v39
	v_mul_f32_e32 v7, v7, v31
	v_fmac_f32_e32 v7, v6, v39
	v_fma_f32 v5, v6, v31, -v5
	v_mul_f32_e32 v6, v42, v7
	v_mul_f32_e32 v7, v1, v40
	v_mul_f32_e32 v1, v1, v32
	v_fma_f32 v7, v0, v32, -v7
	v_fmac_f32_e32 v1, v0, v40
	v_mul_f32_e32 v0, v3, v41
	v_fma_f32 v0, v2, v33, -v0
	v_mul_f32_e32 v27, v42, v0
	v_mul_f32_e32 v0, v3, v33
	v_mul_f32_e32 v7, v42, v7
	v_fmac_f32_e32 v0, v2, v41
	v_mul_f32_e32 v43, v42, v43
	v_mul_f32_e32 v23, v42, v23
	v_mul_f32_e32 v25, v42, v25
	v_mul_f32_e32 v9, v42, v9
	v_mul_f32_e32 v11, v42, v11
	v_mul_f32_e32 v5, v42, v5
	v_mul_f32_e32 v26, v42, v1
	v_mul_f32_e32 v28, v42, v0
	v_cvt_pk_bf16_f32 v0, v43, v23
	v_cvt_pk_bf16_f32 v1, v25, v9
	v_cvt_pk_bf16_f32 v2, v11, v5
	v_cvt_pk_bf16_f32 v3, v7, v27
	v_mul_lo_u32 v7, v13, s66
	v_add3_u32 v5, 32, v7, v160
	v_mov_b32_e32 v13, v161
	ds_write_b128 v5, v[0:3]
	v_cvt_pk_bf16_f32 v0, v22, v24
	v_cvt_pk_bf16_f32 v1, v8, v10
	v_cvt_pk_bf16_f32 v2, v4, v6
	v_cvt_pk_bf16_f32 v3, v26, v28
	ds_write_b128 v5, v[0:3] offset:128
	v_lshl_add_u64 v[4:5], v[16:17], 0, v[12:13]
	v_add_u32_e32 v6, v19, v7
	s_waitcnt vmcnt(9)
	v_mov_b32_e32 v0, v124
	v_mov_b32_e32 v1, v125
	v_mov_b32_e32 v2, v126
	v_mov_b32_e32 v3, v127
	ds_write_b128 v6, v[0:3] offset:34816
	s_waitcnt vmcnt(8)
	v_mov_b32_e32 v0, v128
	v_mov_b32_e32 v1, v129
	v_mov_b32_e32 v2, v130
	v_mov_b32_e32 v3, v131
	ds_write_b128 v6, v[0:3] offset:34832
	v_add_u32_e32 v0, 0x200, v18
	v_ashrrev_i32_e32 v24, 3, v0
	v_add_u32_e32 v0, s11, v24
	v_mad_i64_i32 v[0:1], s[0:1], v0, s65, v[14:15]
	v_lshl_add_u64 v[0:1], v[0:1], 0, s[2:3]
	v_lshl_add_u64 v[6:7], v[0:1], 0, v[160:161]
	s_and_b32 s0, s8, 0x3ff00
	s_lshl_b32 s1, s10, 2
	s_or_b32 s0, s1, s0
	s_or_b32 s0, s0, s9
	s_lshl_b32 s2, s0, 14
	s_lshl_b64 s[0:1], s[2:3], 1
	v_readlane_b32 s2, v253, 28
	s_add_u32 s0, s2, s0
	v_readlane_b32 s2, v253, 29
	s_addc_u32 s1, s2, s1
	s_waitcnt vmcnt(7)
	v_mov_b32_e32 v2, v132
	v_mov_b32_e32 v3, v133
	v_mov_b32_e32 v4, v134
	v_mov_b32_e32 v5, v135
	v_lshlrev_b32_e32 v25, 16, v2
	v_and_b32_e32 v26, 0xffff0000, v2
	v_lshlrev_b32_e32 v27, 16, v3
	v_and_b32_e32 v28, 0xffff0000, v3
	v_lshlrev_b32_e32 v29, 16, v4
	v_and_b32_e32 v30, 0xffff0000, v4
	v_lshlrev_b32_e32 v31, 16, v5
	v_and_b32_e32 v32, 0xffff0000, v5
	s_waitcnt vmcnt(6)
	v_mov_b32_e32 v2, v136
	v_mov_b32_e32 v3, v137
	v_mov_b32_e32 v4, v138
	v_mov_b32_e32 v5, v139
	v_lshlrev_b32_e32 v33, 16, v2
	v_and_b32_e32 v34, 0xffff0000, v2
	v_sub_u32_e32 v2, 0x7f, v24
	v_cvt_f32_i32_e32 v2, v2
	v_lshlrev_b32_e32 v35, 16, v3
	v_and_b32_e32 v36, 0xffff0000, v3
	v_lshlrev_b32_e32 v37, 16, v4
	v_mul_f32_e32 v2, v21, v2
	v_mul_f32_e32 v2, 0x3fb8aa3b, v2
	v_exp_f32_e32 v2, v2
	v_and_b32_e32 v38, 0xffff0000, v4
	v_lshlrev_b32_e32 v39, 16, v5
	v_and_b32_e32 v40, 0xffff0000, v5
	v_mul_f32_e32 v41, 0x3db504f3, v2
	v_lshl_or_b32 v2, v24, 6, v20
	v_ashrrev_i32_e32 v3, 31, v2
	v_lshl_add_u64 v[10:11], v[2:3], 3, s[4:5]
	s_waitcnt vmcnt(2)
	v_mov_b32_e32 v2, v140
	v_mov_b32_e32 v3, v141
	v_mov_b32_e32 v4, v142
	v_mov_b32_e32 v5, v143
	v_mov_b32_e32 v6, v144
	v_mov_b32_e32 v7, v145
	v_mov_b32_e32 v8, v146
	v_mov_b32_e32 v9, v147
	v_mov_b32_e32 v14, v148
	v_mov_b32_e32 v15, v149
	v_mov_b32_e32 v16, v150
	v_mov_b32_e32 v17, v151
	v_mov_b32_e32 v20, v152
	v_mov_b32_e32 v21, v153
	v_mov_b32_e32 v22, v154
	v_mov_b32_e32 v23, v155
	v_mul_f32_e32 v10, v21, v33
	v_mul_f32_e32 v11, v21, v25
	v_fma_f32 v10, v20, v25, -v10
	v_fmac_f32_e32 v11, v20, v33
	v_mul_f32_e32 v20, v23, v34
	v_mul_f32_e32 v21, v23, v26
	v_fma_f32 v20, v22, v26, -v20
	v_fmac_f32_e32 v21, v22, v34
	v_mul_f32_e32 v22, v15, v35
	v_mul_f32_e32 v15, v15, v27
	v_fmac_f32_e32 v15, v14, v35
	v_fma_f32 v22, v14, v27, -v22
	v_mul_f32_e32 v14, v41, v15
	v_mul_f32_e32 v15, v17, v36
	v_mul_f32_e32 v17, v17, v28
	v_fmac_f32_e32 v17, v16, v36
	v_fma_f32 v15, v16, v28, -v15
	v_mul_f32_e32 v16, v41, v17
	v_mul_f32_e32 v17, v7, v37
	v_mul_f32_e32 v7, v7, v29
	v_fmac_f32_e32 v7, v6, v37
	v_fma_f32 v17, v6, v29, -v17
	v_mul_f32_e32 v6, v41, v7
	v_mul_f32_e32 v7, v9, v38
	v_mul_f32_e32 v9, v9, v30
	v_fmac_f32_e32 v9, v8, v38
	v_fma_f32 v7, v8, v30, -v7
	v_mul_f32_e32 v8, v41, v9
	v_mul_f32_e32 v9, v3, v39
	v_mul_f32_e32 v3, v3, v31
	v_fma_f32 v9, v2, v31, -v9
	v_fmac_f32_e32 v3, v2, v39
	v_mul_f32_e32 v2, v5, v40
	v_fma_f32 v2, v4, v32, -v2
	v_mul_f32_e32 v25, v41, v2
	v_mul_f32_e32 v2, v5, v32
	v_mul_f32_e32 v7, v41, v7
	v_fmac_f32_e32 v2, v4, v40
	v_mul_f32_e32 v10, v41, v10
	v_mul_f32_e32 v20, v41, v20
	v_mul_f32_e32 v22, v41, v22
	v_mul_f32_e32 v15, v41, v15
	v_mul_f32_e32 v17, v41, v17
	v_mul_f32_e32 v9, v41, v9
	v_mul_f32_e32 v23, v41, v3
	v_mul_f32_e32 v26, v41, v2
	v_cvt_pk_bf16_f32 v2, v10, v20
	v_cvt_pk_bf16_f32 v3, v22, v15
	v_cvt_pk_bf16_f32 v4, v17, v7
	v_mul_lo_u32 v7, v24, s66
	v_cvt_pk_bf16_f32 v5, v9, v25
	v_add3_u32 v9, 32, v7, v160
	v_mul_f32_e32 v11, v41, v11
	v_mul_f32_e32 v21, v41, v21
	ds_write_b128 v9, v[2:5]
	v_cvt_pk_bf16_f32 v2, v11, v21
	v_cvt_pk_bf16_f32 v3, v14, v16
	v_cvt_pk_bf16_f32 v4, v6, v8
	v_cvt_pk_bf16_f32 v5, v23, v26
	ds_write_b128 v9, v[2:5] offset:128
	v_lshl_add_u64 v[4:5], v[0:1], 0, v[12:13]
	v_add_u32_e32 v6, v19, v7
	s_waitcnt vmcnt(1)
	v_mov_b32_e32 v0, v156
	v_mov_b32_e32 v1, v157
	v_mov_b32_e32 v2, v158
	v_mov_b32_e32 v3, v159
	ds_write_b128 v6, v[0:3] offset:34816
	v_ashrrev_i32_e32 v4, 6, v18
	v_and_b32_e32 v5, 15, v18
	v_lshlrev_b32_e32 v5, 7, v5
	s_waitcnt vmcnt(0)
	v_mov_b32_e32 v0, v204
	v_mov_b32_e32 v1, v205
	v_mov_b32_e32 v2, v206
	v_mov_b32_e32 v3, v207
	ds_write_b128 v6, v[0:3] offset:34832
	v_lshrrev_b32_e32 v0, 1, v18
	v_and_b32_e32 v160, 24, v0
	v_bfe_u32 v0, v18, 2, 2
	v_or_b32_e32 v0, v160, v0
	v_lshlrev_b32_e32 v1, 3, v18
	v_mul_u32_u24_e32 v0, 0x88, v0
	v_and_b32_e32 v1, 24, v1
	v_lshlrev_b32_e32 v0, 1, v0
	v_add3_u32 v6, 32, v1, v0
	v_lshl_add_u32 v7, v4, 5, v6
	s_waitcnt lgkmcnt(0)
	s_barrier
; DI f32x4 mmaT(bf16x8 a_m, bf16x8 b_n, f32x4 c) { return __builtin_amdgcn_mfma_f32_16x16x32_bf16(b_n, a_m, c, 0, 0, 0); }
; DI void ret_local_unit(const Params& p, int hf, int bl, int c, int hd, unsigned char* shm, int tid) {
;     ...
;   const int wid = tid >> 6, lane = tid & 63, fr = lane & 15, fq = lane >> 4;
;   f32x4 acc[8];
; #pragma unroll
;   for (int n = 0; n < 8; ++n) acc[n] = (f32x4){0.f, 0.f, 0.f, 0.f};
; #pragma unroll
;   for (int ks = 0; ks < 4; ++ks) {
;     const bf16x8 a = frag_tr(sV, LD, 32 * ks, 16 * wid, fr, fq);
; #pragma unroll
;     for (int n = 0; n < 8; ++n) acc[n] = mmaT(a, frag_tr(sK, LD, 32 * ks, 16 * n, fr, fq), acc[n]);
;   }
	ds_read_b64_tr_b16 v[0:1], v7 offset:34816
	ds_read_b64_tr_b16 v[2:3], v7 offset:35904
	ds_read_b64_tr_b16 v[10:11], v6 offset:1088
	ds_read_b64_tr_b16 v[8:9], v6
	ds_read_b64_tr_b16 v[12:13], v6 offset:32
	ds_read_b64_tr_b16 v[14:15], v6 offset:1120
	ds_read_b64_tr_b16 v[16:17], v6 offset:64
	ds_read_b64_tr_b16 v[18:19], v6 offset:1152
	ds_read_b64_tr_b16 v[20:21], v6 offset:96
	ds_read_b64_tr_b16 v[22:23], v6 offset:1184
	ds_read_b64_tr_b16 v[24:25], v6 offset:128
	ds_read_b64_tr_b16 v[26:27], v6 offset:1216
	ds_read_b64_tr_b16 v[28:29], v6 offset:160
	ds_read_b64_tr_b16 v[30:31], v6 offset:1248
	ds_read_b64_tr_b16 v[32:33], v6 offset:192
	ds_read_b64_tr_b16 v[34:35], v6 offset:1280
	ds_read_b64_tr_b16 v[36:37], v6 offset:224
	ds_read_b64_tr_b16 v[38:39], v6 offset:1312
	s_waitcnt lgkmcnt(14)
	v_mfma_f32_16x16x32_bf16 v[8:11], v[8:11], v[0:3], 0
	v_lshl_or_b32 v4, v4, 11, v5
	v_ashrrev_i32_e32 v5, 31, v4
	v_lshl_add_u64 v[4:5], v[4:5], 1, s[0:1]
	s_waitcnt lgkmcnt(12)
	v_mfma_f32_16x16x32_bf16 v[12:15], v[12:15], v[0:3], 0
	v_lshl_add_u64 v[4:5], v[4:5], 0, v[160:161]
	s_mov_b64 s[0:1], 0
	s_waitcnt lgkmcnt(10)
	v_mfma_f32_16x16x32_bf16 v[16:19], v[16:19], v[0:3], 0
	s_waitcnt lgkmcnt(8)
	v_mfma_f32_16x16x32_bf16 v[20:23], v[20:23], v[0:3], 0
	s_waitcnt lgkmcnt(6)
	v_mfma_f32_16x16x32_bf16 v[24:27], v[24:27], v[0:3], 0
	s_waitcnt lgkmcnt(4)
	v_mfma_f32_16x16x32_bf16 v[28:31], v[28:31], v[0:3], 0
	s_waitcnt lgkmcnt(2)
	v_mfma_f32_16x16x32_bf16 v[32:35], v[32:35], v[0:3], 0
	s_waitcnt lgkmcnt(0)
	v_mfma_f32_16x16x32_bf16 v[0:3], v[36:39], v[0:3], 0
	ds_read_b64_tr_b16 v[36:37], v7 offset:43520
	ds_read_b64_tr_b16 v[38:39], v7 offset:44608
	ds_read_b64_tr_b16 v[40:41], v6 offset:8704
	ds_read_b64_tr_b16 v[42:43], v6 offset:9792
	s_waitcnt lgkmcnt(0)
	v_mfma_f32_16x16x32_bf16 v[8:11], v[40:43], v[36:39], v[8:11]
	ds_read_b64_tr_b16 v[40:41], v6 offset:8736
	ds_read_b64_tr_b16 v[42:43], v6 offset:9824
	s_waitcnt lgkmcnt(0)
	v_mfma_f32_16x16x32_bf16 v[12:15], v[40:43], v[36:39], v[12:15]
	ds_read_b64_tr_b16 v[40:41], v6 offset:8768
	ds_read_b64_tr_b16 v[42:43], v6 offset:9856
	s_waitcnt lgkmcnt(0)
	v_mfma_f32_16x16x32_bf16 v[16:19], v[40:43], v[36:39], v[16:19]
	ds_read_b64_tr_b16 v[40:41], v6 offset:8800
	ds_read_b64_tr_b16 v[42:43], v6 offset:9888
	s_waitcnt lgkmcnt(0)
	v_mfma_f32_16x16x32_bf16 v[20:23], v[40:43], v[36:39], v[20:23]
	ds_read_b64_tr_b16 v[40:41], v6 offset:8832
	ds_read_b64_tr_b16 v[42:43], v6 offset:9920
	s_waitcnt lgkmcnt(0)
	v_mfma_f32_16x16x32_bf16 v[24:27], v[40:43], v[36:39], v[24:27]
	ds_read_b64_tr_b16 v[40:41], v6 offset:8864
	ds_read_b64_tr_b16 v[42:43], v6 offset:9952
	s_waitcnt lgkmcnt(0)
	v_mfma_f32_16x16x32_bf16 v[28:31], v[40:43], v[36:39], v[28:31]
	ds_read_b64_tr_b16 v[40:41], v6 offset:8896
	ds_read_b64_tr_b16 v[42:43], v6 offset:9984
	s_waitcnt lgkmcnt(0)
	v_mfma_f32_16x16x32_bf16 v[32:35], v[40:43], v[36:39], v[32:35]
	ds_read_b64_tr_b16 v[40:41], v6 offset:8928
	ds_read_b64_tr_b16 v[42:43], v6 offset:10016
	s_waitcnt lgkmcnt(0)
	v_mfma_f32_16x16x32_bf16 v[0:3], v[40:43], v[36:39], v[0:3]
	ds_read_b64_tr_b16 v[36:37], v7 offset:52224
	ds_read_b64_tr_b16 v[38:39], v7 offset:53312
	ds_read_b64_tr_b16 v[40:41], v6 offset:17408
	ds_read_b64_tr_b16 v[42:43], v6 offset:18496
	s_waitcnt lgkmcnt(0)
	v_mfma_f32_16x16x32_bf16 v[8:11], v[40:43], v[36:39], v[8:11]
	ds_read_b64_tr_b16 v[40:41], v6 offset:17440
	ds_read_b64_tr_b16 v[42:43], v6 offset:18528
	s_waitcnt lgkmcnt(0)
; DI unsigned pk2(float lo, float hi) { unsigned r; asm volatile("v_cvt_pk_bf16_f32 %0, %1, %2" : "=v"(r) : "v"(lo), "v"(hi)); return r; }
; DI f32x4 mmaT(bf16x8 a_m, bf16x8 b_n, f32x4 c) { return __builtin_amdgcn_mfma_f32_16x16x32_bf16(b_n, a_m, c, 0, 0, 0); }
; DI void ret_local_unit(const Params& p, int hf, int bl, int c, int hd, unsigned char* shm, int tid) {
;     ...
; #pragma unroll
;   for (int ks = 0; ks < 4; ++ks) {
;     const bf16x8 a = frag_tr(sV, LD, 32 * ks, 16 * wid, fr, fq);
; #pragma unroll
;     for (int n = 0; n < 8; ++n) acc[n] = mmaT(a, frag_tr(sK, LD, 32 * ks, 16 * n, fr, fq), acc[n]);
;   }
;   bf16_t* st = (bf16_t*)(wsb + WS_RST) + (size_t)((bl * 64 + c) * 4 + hd) * 16384;
; #pragma unroll
;   for (int n = 0; n < 8; ++n) { uint2 w; w.x = pk2(acc[n][0], acc[n][1]); w.y = pk2(acc[n][2], acc[n][3]); *(uint2*)(st + (16 * wid + fr) * 128 + 16 * n + 4 * fq) = w; }
;   __syncthreads();
	v_mfma_f32_16x16x32_bf16 v[12:15], v[40:43], v[36:39], v[12:15]
	ds_read_b64_tr_b16 v[40:41], v6 offset:17472
	ds_read_b64_tr_b16 v[42:43], v6 offset:18560
	s_waitcnt lgkmcnt(0)
	v_mfma_f32_16x16x32_bf16 v[16:19], v[40:43], v[36:39], v[16:19]
	ds_read_b64_tr_b16 v[40:41], v6 offset:17504
	ds_read_b64_tr_b16 v[42:43], v6 offset:18592
	s_waitcnt lgkmcnt(0)
	v_mfma_f32_16x16x32_bf16 v[20:23], v[40:43], v[36:39], v[20:23]
	ds_read_b64_tr_b16 v[40:41], v6 offset:17536
	ds_read_b64_tr_b16 v[42:43], v6 offset:18624
	s_waitcnt lgkmcnt(0)
	v_mfma_f32_16x16x32_bf16 v[24:27], v[40:43], v[36:39], v[24:27]
	ds_read_b64_tr_b16 v[40:41], v6 offset:17568
	ds_read_b64_tr_b16 v[42:43], v6 offset:18656
	s_waitcnt lgkmcnt(0)
	v_mfma_f32_16x16x32_bf16 v[28:31], v[40:43], v[36:39], v[28:31]
	ds_read_b64_tr_b16 v[40:41], v6 offset:17600
	ds_read_b64_tr_b16 v[42:43], v6 offset:18688
	s_waitcnt lgkmcnt(0)
	v_mfma_f32_16x16x32_bf16 v[32:35], v[40:43], v[36:39], v[32:35]
	ds_read_b64_tr_b16 v[40:41], v6 offset:17632
	ds_read_b64_tr_b16 v[42:43], v6 offset:18720
	s_waitcnt lgkmcnt(0)
	v_mfma_f32_16x16x32_bf16 v[0:3], v[40:43], v[36:39], v[0:3]
	ds_read_b64_tr_b16 v[36:37], v7 offset:60928
	ds_read_b64_tr_b16 v[38:39], v7 offset:62016
	ds_read_b64_tr_b16 v[40:41], v6 offset:26112
	ds_read_b64_tr_b16 v[42:43], v6 offset:27200
	s_waitcnt lgkmcnt(0)
	v_mfma_f32_16x16x32_bf16 v[8:11], v[40:43], v[36:39], v[8:11]
	ds_read_b64_tr_b16 v[40:41], v6 offset:26144
	ds_read_b64_tr_b16 v[42:43], v6 offset:27232
	s_waitcnt lgkmcnt(0)
	v_mfma_f32_16x16x32_bf16 v[12:15], v[40:43], v[36:39], v[12:15]
	ds_read_b64_tr_b16 v[40:41], v6 offset:26176
	ds_read_b64_tr_b16 v[42:43], v6 offset:27264
	s_waitcnt lgkmcnt(0)
	v_mfma_f32_16x16x32_bf16 v[16:19], v[40:43], v[36:39], v[16:19]
	ds_read_b64_tr_b16 v[40:41], v6 offset:26208
	ds_read_b64_tr_b16 v[42:43], v6 offset:27296
	s_waitcnt lgkmcnt(0)
	v_mfma_f32_16x16x32_bf16 v[20:23], v[40:43], v[36:39], v[20:23]
	ds_read_b64_tr_b16 v[40:41], v6 offset:26240
	ds_read_b64_tr_b16 v[42:43], v6 offset:27328
	s_waitcnt lgkmcnt(0)
	v_mfma_f32_16x16x32_bf16 v[24:27], v[40:43], v[36:39], v[24:27]
	ds_read_b64_tr_b16 v[40:41], v6 offset:26272
	ds_read_b64_tr_b16 v[42:43], v6 offset:27360
	s_waitcnt lgkmcnt(0)
	v_mfma_f32_16x16x32_bf16 v[28:31], v[40:43], v[36:39], v[28:31]
	ds_read_b64_tr_b16 v[40:41], v6 offset:26304
	ds_read_b64_tr_b16 v[42:43], v6 offset:27392
	s_waitcnt lgkmcnt(0)
	v_mfma_f32_16x16x32_bf16 v[32:35], v[40:43], v[36:39], v[32:35]
	ds_read_b64_tr_b16 v[40:41], v6 offset:26336
	ds_read_b64_tr_b16 v[42:43], v6 offset:27424
	v_cvt_pk_bf16_f32 v6, v8, v9
	v_cvt_pk_bf16_f32 v7, v10, v11
	global_store_dwordx2 v[4:5], v[6:7], off
	v_cvt_pk_bf16_f32 v6, v12, v13
	v_cvt_pk_bf16_f32 v7, v14, v15
	global_store_dwordx2 v[4:5], v[6:7], off offset:32
	v_cvt_pk_bf16_f32 v6, v16, v17
	v_cvt_pk_bf16_f32 v7, v18, v19
	global_store_dwordx2 v[4:5], v[6:7], off offset:64
	v_cvt_pk_bf16_f32 v6, v20, v21
	v_cvt_pk_bf16_f32 v7, v22, v23
	global_store_dwordx2 v[4:5], v[6:7], off offset:96
	v_cvt_pk_bf16_f32 v6, v24, v25
	v_cvt_pk_bf16_f32 v7, v26, v27
	s_waitcnt lgkmcnt(0)
	v_mfma_f32_16x16x32_bf16 v[0:3], v[40:43], v[36:39], v[0:3]
	global_store_dwordx2 v[4:5], v[6:7], off offset:128
	v_cvt_pk_bf16_f32 v6, v28, v29
	v_cvt_pk_bf16_f32 v7, v30, v31
	global_store_dwordx2 v[4:5], v[6:7], off offset:160
	v_cvt_pk_bf16_f32 v6, v32, v33
	v_cvt_pk_bf16_f32 v7, v34, v35
	global_store_dwordx2 v[4:5], v[6:7], off offset:192
	v_cvt_pk_bf16_f32 v0, v0, v1
	v_cvt_pk_bf16_f32 v1, v2, v3
	s_nop 4
	global_store_dwordx2 v[4:5], v[0:1], off offset:224
	s_barrier

; DI void unpack8(uint4 v, float* f) { f[0] = bflo(v.x); f[1] = bfhi(v.x); f[2] = bflo(v.y); f[3] = bfhi(v.y); f[4] = bflo(v.z); f[5] = bfhi(v.z); f[6] = bflo(v.w); f[7] = bfhi(v.w); }
; DI float shx(float v, int m, int lane) { return __int_as_float(__builtin_amdgcn_ds_bpermute((lane ^ m) << 2, __float_as_int(v))); }
; DI void fox_cumsum_unit(const Params& p, int hf, int bl, int fh, unsigned char* shm, int tid) {
;     ...
;   const bf16_t* kb = (const bf16_t*)(wsb + WS_PROJ) + (size_t)(bl * SEQ + tid * 16) * NP + C_FK + fh * 64;
;   float kmx = 0.f;
; #pragma unroll 4
;   for (int e = 0; e < 16; ++e) {
;     float ssum = 0.f;
; #pragma unroll
;     for (int q = 0; q < 8; ++q) { float f[8]; unpack8(*(const uint4*)(kb + (size_t)e * NP + q * 8), f);
; #pragma unroll
;       for (int z = 0; z < 8; ++z) ssum += f[z] * f[z]; }
;     kmx = fmaxf(kmx, ssum);
;   }
; #pragma unroll
;   for (int o = 32; o >= 1; o >>= 1) kmx = fmaxf(kmx, shx(kmx, o, lane));
.Lkmx_unit:
	s_add_i32 s4, s24, 0xfffffcf0
	s_mov_b32 s5, 0
	s_lshr_b32 s0, s4, 5
	s_lshl_b32 s0, s0, 13
	s_and_b32 s6, s4, 3
	s_lshl_b32 s6, s6, 11
	s_add_i32 s0, s0, s6
	s_bfe_u32 s2, s4, 0x30002
	v_mov_b32_e32 v46, v163
	v_ashrrev_i32_e32 v1, 6, v46
	v_lshl_add_u32 v48, v1, 2, 32
	v_and_b32_e32 v18, 63, v46
	v_lshlrev_b32_e32 v47, 2, v18
	s_waitcnt vmcnt(0)
	v_lshrrev_b32_e32 v0, 3, v46
	v_and_b32_e32 v1, 7, v46
	v_mul_u32_u24_e32 v0, 0x3400, v0
	v_lshl_add_u32 v49, v1, 4, v0
	s_mul_hi_u32 s1, s0, 0x3400
	s_mul_i32 s0, s0, 0x3400
	s_lshl_b32 s6, s2, 7
	s_add_u32 s0, s0, s6
	s_addc_u32 s1, s1, 0
	s_add_u32 s0, s0, 0x1c00
	s_addc_u32 s1, s1, 0
	s_add_u32 s10, s38, s0
	s_addc_u32 s11, s39, s1
	v_mov_b32_e32 v14, 0
	global_load_dwordx4 v[50:53], v49, s[10:11]
	s_add_u32 s10, s10, 0xd0000
	s_addc_u32 s11, s11, 0
	global_load_dwordx4 v[54:57], v49, s[10:11]
	s_add_u32 s10, s10, 0xd0000
	s_addc_u32 s11, s11, 0
	global_load_dwordx4 v[58:61], v49, s[10:11]
	s_add_u32 s10, s10, 0xd0000
	s_addc_u32 s11, s11, 0
	global_load_dwordx4 v[62:65], v49, s[10:11]
	s_add_u32 s10, s10, 0xd0000
	s_addc_u32 s11, s11, 0
	global_load_dwordx4 v[66:69], v49, s[10:11]
	s_add_u32 s10, s10, 0xd0000
	s_addc_u32 s11, s11, 0
	global_load_dwordx4 v[70:73], v49, s[10:11]
	s_add_u32 s10, s10, 0xd0000
	s_addc_u32 s11, s11, 0
	global_load_dwordx4 v[74:77], v49, s[10:11]
	s_add_u32 s10, s10, 0xd0000
	s_addc_u32 s11, s11, 0
	global_load_dwordx4 v[78:81], v49, s[10:11]
	s_add_u32 s10, s10, 0xd0000
	s_addc_u32 s11, s11, 0
	global_load_dwordx4 v[82:85], v49, s[10:11]
	s_add_u32 s10, s10, 0xd0000
	s_addc_u32 s11, s11, 0
	global_load_dwordx4 v[86:89], v49, s[10:11]
	s_add_u32 s10, s10, 0xd0000
	s_addc_u32 s11, s11, 0
	global_load_dwordx4 v[90:93], v49, s[10:11]
	s_add_u32 s10, s10, 0xd0000
	s_addc_u32 s11, s11, 0
	global_load_dwordx4 v[94:97], v49, s[10:11]
	s_add_u32 s10, s10, 0xd0000
	s_addc_u32 s11, s11, 0
	global_load_dwordx4 v[98:101], v49, s[10:11]
	s_add_u32 s10, s10, 0xd0000
	s_addc_u32 s11, s11, 0
	global_load_dwordx4 v[102:105], v49, s[10:11]
	s_add_u32 s10, s10, 0xd0000
	s_addc_u32 s11, s11, 0
	global_load_dwordx4 v[106:109], v49, s[10:11]
	s_add_u32 s10, s10, 0xd0000
	s_addc_u32 s11, s11, 0
	global_load_dwordx4 v[110:113], v49, s[10:11]
	s_add_u32 s10, s10, 0xd0000
	s_addc_u32 s11, s11, 0
	s_mov_b32 s9, 1

; DI void fox_unit(const Params& p, int hf, int bl, int fh, int qb, unsigned char* shm, int tid, bool dry = false) {
;     ...
;   const float Fref = F[q0];
;   __syncthreads();
;   float qm2 = 0.f;
; #pragma unroll
;   for (int i = 0; i < 8; ++i) qm2 = fmaxf(qm2, sRed[i]);
;   const float kmax2 = ((const float*)(wsb + WS_KMAX))[bl * 8 + fh];
;   const float thr = -110.0f - 0.25f * sqrtf(qm2 * kmax2) * 1.02f;
;   const int nkt = 4 * qb + 4;
;   int skip = 0;
;   if (tid < 4 * qb) skip = (Fref - F[tid * 64 + 63] < thr) ? 1 : 0;
;   const unsigned long long bal = __builtin_amdgcn_ballot_w64(skip != 0);
;   if (lane == 0) ((int*)sRed)[8 + wid] = __builtin_popcountll(bal);
.LBB0_471:
	s_or_b64 exec, exec, s[0:1]
	s_and_b32 s12, s23, 15
	s_lshl_b32 s0, s12, 15
	v_readlane_b32 s1, v253, 34
	s_add_u32 s8, s1, s0
	v_readlane_b32 s0, v253, 35
	s_addc_u32 s9, s0, 0
	s_lshl_b32 s0, s5, 2
	v_mov_b32_e32 v17, s0
	global_load_dword v192, v17, s[8:9]
	s_lshl_b32 s17, s4, 2
	v_cmp_gt_i32_e64 s[0:1], s17, v205
	s_mov_b64 s[4:5], 0
	s_waitcnt lgkmcnt(0)
	s_barrier
	s_and_saveexec_b64 s[10:11], s[0:1]
	s_cbranch_execz .LBB0_473
	ds_read_b128 v[18:21], v203 offset:37376
	ds_read_b128 v[30:33], v203 offset:37392
	s_lshl_b32 s0, s12, 4
	s_waitcnt lgkmcnt(1)
	v_max3_f32 v17, v18, 0, v19
	v_max3_f32 v17, v17, v20, v21
	v_mov_b32_e32 v20, s0
	v_readlane_b32 s0, v253, 36
	v_readlane_b32 s1, v253, 37
	s_waitcnt lgkmcnt(0)
	v_max3_f32 v17, v17, v30, v31
	v_max3_f32 v17, v17, v32, v33
	v_lshlrev_b32_e32 v18, 6, v205
	v_ashrrev_i32_e32 v19, 31, v18
	v_lshl_add_u64 v[18:19], v[18:19], 2, s[8:9]
	global_load_dwordx4 v[30:33], v20, s[0:1]
	s_mov_b32 s0, 0xf800000
	s_waitcnt vmcnt(0)
	v_max3_f32 v20, v30, v31, v32
	v_max_f32_e32 v20, v20, v33
	v_mul_f32_e32 v17, v17, v20
	v_cmp_gt_f32_e64 s[0:1], s0, v17
	v_mul_f32_e32 v20, 0x4f800000, v17
	s_nop 0
	v_cndmask_b32_e64 v17, v17, v20, s[0:1]
	v_sqrt_f32_e32 v20, v17
	s_nop 0
	v_add_u32_e32 v21, -1, v20
	v_fma_f32 v22, -v21, v20, v17
	v_cmp_ge_f32_e64 s[4:5], 0, v22
	v_add_u32_e32 v22, 1, v20
	s_nop 0
	v_cndmask_b32_e64 v21, v20, v21, s[4:5]
	v_fma_f32 v20, -v22, v20, v17
	v_cmp_lt_f32_e64 s[4:5], 0, v20
	s_nop 1
	v_cndmask_b32_e64 v20, v21, v22, s[4:5]
	v_mul_f32_e32 v21, 0x37800000, v20
	v_cndmask_b32_e64 v20, v20, v21, s[0:1]
	v_mov_b32_e32 v21, 0x260
	v_cmp_class_f32_e64 s[0:1], v17, v21
	s_nop 1
	v_cndmask_b32_e64 v17, v20, v17, s[0:1]
	global_load_dword v20, v[18:19], off offset:252
	v_mul_f32_e32 v17, 0x3e800000, v17
	v_mul_f32_e32 v21, 0x3f828f5c, v17
	s_waitcnt vmcnt(0)
	v_pk_add_f32 v[18:19], v[192:193], v[20:21] neg_lo:[0,1] neg_hi:[0,1]
	s_nop 0
	v_cmp_lt_f32_e64 s[0:1], v18, v19
	s_and_b64 s[4:5], s[0:1], exec

; DI void fox_unit(const Params& p, int hf, int bl, int fh, int qb, unsigned char* shm, int tid, bool dry = false) {
;     ...
;   const float Fref = F[q0];
;   __syncthreads();
;   float qm2 = 0.f;
; #pragma unroll
;   for (int i = 0; i < 8; ++i) qm2 = fmaxf(qm2, sRed[i]);
;   const float kmax2 = ((const float*)(wsb + WS_KMAX))[bl * 8 + fh];
;   const float thr = -110.0f - 0.25f * sqrtf(qm2 * kmax2) * 1.02f;
;   const int nkt = 4 * qb + 4;
;   int skip = 0;
;   if (tid < 4 * qb) skip = (Fref - F[tid * 64 + 63] < thr) ? 1 : 0;
;   const unsigned long long bal = __builtin_amdgcn_ballot_w64(skip != 0);
;   if (lane == 0) ((int*)sRed)[8 + wid] = __builtin_popcountll(bal);
.LBB0_591:
	s_or_b64 exec, exec, s[4:5]
	s_and_b32 s12, s23, 15
	s_lshl_b32 s1, s12, 15
	v_readlane_b32 s4, v253, 34
	s_add_u32 s8, s4, s1
	v_readlane_b32 s1, v253, 35
	s_addc_u32 s9, s1, 0
	s_mov_b32 s1, s3
	s_lshl_b64 s[0:1], s[0:1], 2
	s_add_u32 s0, s8, s0
	s_addc_u32 s1, s9, s1
	global_load_dword v192, v161, s[0:1]
	s_lshl_b32 s16, s10, 2
	v_cmp_gt_i32_e64 s[0:1], s16, v205
	s_mov_b64 s[4:5], 0
	s_waitcnt lgkmcnt(0)
	s_barrier
	s_and_saveexec_b64 s[10:11], s[0:1]
	s_cbranch_execz .LBB0_593
	ds_read_b128 v[18:21], v203 offset:37376
	ds_read_b128 v[30:33], v203 offset:37392
	s_lshl_b32 s0, s12, 4
	s_waitcnt lgkmcnt(1)
	v_max3_f32 v17, v18, 0, v19
	v_max3_f32 v17, v17, v20, v21
	v_mov_b32_e32 v20, s0
	v_readlane_b32 s0, v253, 36
	v_readlane_b32 s1, v253, 37
	s_waitcnt lgkmcnt(0)
	v_max3_f32 v17, v17, v30, v31
	v_max3_f32 v17, v17, v32, v33
	v_lshlrev_b32_e32 v18, 6, v205
	v_ashrrev_i32_e32 v19, 31, v18
	v_lshl_add_u64 v[18:19], v[18:19], 2, s[8:9]
	global_load_dwordx4 v[30:33], v20, s[0:1]
	s_mov_b32 s0, 0xf800000
	s_waitcnt vmcnt(0)
	v_max3_f32 v20, v30, v31, v32
	v_max_f32_e32 v20, v20, v33
	v_mul_f32_e32 v17, v17, v20
	v_cmp_gt_f32_e64 s[0:1], s0, v17
	v_mul_f32_e32 v20, 0x4f800000, v17
	s_nop 0
	v_cndmask_b32_e64 v17, v17, v20, s[0:1]
	v_sqrt_f32_e32 v20, v17
	s_nop 0
	v_add_u32_e32 v21, -1, v20
	v_fma_f32 v22, -v21, v20, v17
	v_cmp_ge_f32_e64 s[4:5], 0, v22
	v_add_u32_e32 v22, 1, v20
	s_nop 0
	v_cndmask_b32_e64 v21, v20, v21, s[4:5]
	v_fma_f32 v20, -v22, v20, v17
	v_cmp_lt_f32_e64 s[4:5], 0, v20
	s_nop 1
	v_cndmask_b32_e64 v20, v21, v22, s[4:5]
	v_mul_f32_e32 v21, 0x37800000, v20
	v_cndmask_b32_e64 v20, v20, v21, s[0:1]
	v_mov_b32_e32 v21, 0x260
	v_cmp_class_f32_e64 s[0:1], v17, v21
	s_nop 1
	v_cndmask_b32_e64 v17, v20, v17, s[0:1]
	global_load_dword v20, v[18:19], off offset:252
	v_mul_f32_e32 v17, 0x3e800000, v17
	v_mul_f32_e32 v21, 0x3f828f5c, v17
	s_waitcnt vmcnt(0)
	v_pk_add_f32 v[18:19], v[192:193], v[20:21] neg_lo:[0,1] neg_hi:[0,1]
	s_nop 0
	v_cmp_lt_f32_e64 s[0:1], v18, v19
	s_and_b64 s[4:5], s[0:1], exec
